# phase_up epilogue by hand: dwordx4 stores via v_permlane16_swap (16 instead of 32 stores per wave), no canonicalizing max
# speedup vs baseline: 1.0114x; 1.0098x over previous
.LBB0_1584:
	s_waitcnt vmcnt(0)
	s_waitcnt lgkmcnt(0)
	v_lshl_or_b32 v133, s18, 7, v171
	v_lshlrev_b32_e32 v0, 2, v170
	s_waitcnt lgkmcnt(0)
	s_barrier
	v_lshl_or_b32 v134, s17, 6, v0
	v_add_u32_e32 v206, s15, v133
	v_mad_i64_i32 v[204:205], s[0:1], v206, s13, 0
	v_or_b32_e32 v0, s16, v134
	v_lshlrev_b32_e32 v0, 1, v0
	v_and_b32_e32 v207, 1, v170
	v_mul_u32_u24_e32 v207, 24, v207
	v_add_u32_e32 v0, v0, v207
	v_lshl_add_u64 v[204:205], s[96:97], 0, v[204:205]
	v_lshl_add_u64 v[204:205], v[204:205], 0, v[0:1]
	s_lshl_b32 s0, s13, 4
	v_mov_b32_e32 v208, s0
	v_mov_b32_e32 v209, 0
	v_max_f32_e32 v126, 0, v126
	v_max_f32_e32 v127, 0, v127
	v_max_f32_e32 v128, 0, v128
	v_max_f32_e32 v129, 0, v129
	v_mul_f32_e32 v126, v126, v126
	v_mul_f32_e32 v127, v127, v127
	v_mul_f32_e32 v128, v128, v128
	v_mul_f32_e32 v129, v129, v129
	v_max_f32_e32 v122, 0, v122
	v_max_f32_e32 v123, 0, v123
	v_max_f32_e32 v124, 0, v124
	v_max_f32_e32 v125, 0, v125
	v_mul_f32_e32 v122, v122, v122
	v_mul_f32_e32 v123, v123, v123
	v_mul_f32_e32 v124, v124, v124
	v_mul_f32_e32 v125, v125, v125
	v_max_f32_e32 v118, 0, v118
	v_max_f32_e32 v119, 0, v119
	v_max_f32_e32 v120, 0, v120
	v_max_f32_e32 v121, 0, v121
	v_mul_f32_e32 v118, v118, v118
	v_mul_f32_e32 v119, v119, v119
	v_mul_f32_e32 v120, v120, v120
	v_mul_f32_e32 v121, v121, v121
	v_max_f32_e32 v114, 0, v114
	v_max_f32_e32 v115, 0, v115
	v_max_f32_e32 v116, 0, v116
	v_max_f32_e32 v117, 0, v117
	v_mul_f32_e32 v114, v114, v114
	v_mul_f32_e32 v115, v115, v115
	v_mul_f32_e32 v116, v116, v116
	v_mul_f32_e32 v117, v117, v117
	v_cvt_pk_bf16_f32 v196, v126, v127
	v_cvt_pk_bf16_f32 v197, v128, v129
	v_cvt_pk_bf16_f32 v198, v122, v123
	v_cvt_pk_bf16_f32 v199, v124, v125
	v_cvt_pk_bf16_f32 v200, v118, v119
	v_cvt_pk_bf16_f32 v201, v120, v121
	v_cvt_pk_bf16_f32 v202, v114, v115
	v_cvt_pk_bf16_f32 v203, v116, v117
	v_cmp_gt_i32_e32 vcc, s12, v206
	s_nop 0
	v_permlane16_swap_b32_e32 v196, v198
	v_permlane16_swap_b32_e32 v197, v199
	v_permlane16_swap_b32_e32 v200, v202
	v_permlane16_swap_b32_e32 v201, v203
	s_and_saveexec_b64 s[0:1], vcc
	global_store_dwordx4 v[204:205], v[196:199], off
	global_store_dwordx4 v[204:205], v[200:203], off offset:64
	s_or_b64 exec, exec, s[0:1]
	v_lshl_add_u64 v[204:205], v[204:205], 0, v[208:209]
	v_add_u32_e32 v206, 16, v206
	v_max_f32_e32 v110, 0, v110
	v_max_f32_e32 v111, 0, v111
	v_max_f32_e32 v112, 0, v112
	v_max_f32_e32 v113, 0, v113
	v_mul_f32_e32 v110, v110, v110
	v_mul_f32_e32 v111, v111, v111
	v_mul_f32_e32 v112, v112, v112
	v_mul_f32_e32 v113, v113, v113
	v_max_f32_e32 v106, 0, v106
	v_max_f32_e32 v107, 0, v107
	v_max_f32_e32 v108, 0, v108
	v_max_f32_e32 v109, 0, v109
	v_mul_f32_e32 v106, v106, v106
	v_mul_f32_e32 v107, v107, v107
	v_mul_f32_e32 v108, v108, v108
	v_mul_f32_e32 v109, v109, v109
	v_max_f32_e32 v102, 0, v102
	v_max_f32_e32 v103, 0, v103
	v_max_f32_e32 v104, 0, v104
	v_max_f32_e32 v105, 0, v105
	v_mul_f32_e32 v102, v102, v102
	v_mul_f32_e32 v103, v103, v103
	v_mul_f32_e32 v104, v104, v104
	v_mul_f32_e32 v105, v105, v105
	v_max_f32_e32 v98, 0, v98
	v_max_f32_e32 v99, 0, v99
	v_max_f32_e32 v100, 0, v100
	v_max_f32_e32 v101, 0, v101
	v_mul_f32_e32 v98, v98, v98
	v_mul_f32_e32 v99, v99, v99
	v_mul_f32_e32 v100, v100, v100
	v_mul_f32_e32 v101, v101, v101
	v_cvt_pk_bf16_f32 v196, v110, v111
	v_cvt_pk_bf16_f32 v197, v112, v113
	v_cvt_pk_bf16_f32 v198, v106, v107
	v_cvt_pk_bf16_f32 v199, v108, v109
	v_cvt_pk_bf16_f32 v200, v102, v103
	v_cvt_pk_bf16_f32 v201, v104, v105
	v_cvt_pk_bf16_f32 v202, v98, v99
	v_cvt_pk_bf16_f32 v203, v100, v101
	v_cmp_gt_i32_e32 vcc, s12, v206
	s_nop 0
	v_permlane16_swap_b32_e32 v196, v198
	v_permlane16_swap_b32_e32 v197, v199
	v_permlane16_swap_b32_e32 v200, v202
	v_permlane16_swap_b32_e32 v201, v203
	s_and_saveexec_b64 s[0:1], vcc
	global_store_dwordx4 v[204:205], v[196:199], off
	global_store_dwordx4 v[204:205], v[200:203], off offset:64
	s_or_b64 exec, exec, s[0:1]
	v_lshl_add_u64 v[204:205], v[204:205], 0, v[208:209]
	v_add_u32_e32 v206, 16, v206
	v_max_f32_e32 v94, 0, v94
	v_max_f32_e32 v95, 0, v95
	v_max_f32_e32 v96, 0, v96
	v_max_f32_e32 v97, 0, v97
	v_mul_f32_e32 v94, v94, v94
	v_mul_f32_e32 v95, v95, v95
	v_mul_f32_e32 v96, v96, v96
	v_mul_f32_e32 v97, v97, v97
	v_max_f32_e32 v90, 0, v90
	v_max_f32_e32 v91, 0, v91
	v_max_f32_e32 v92, 0, v92
	v_max_f32_e32 v93, 0, v93
	v_mul_f32_e32 v90, v90, v90
	v_mul_f32_e32 v91, v91, v91
	v_mul_f32_e32 v92, v92, v92
	v_mul_f32_e32 v93, v93, v93
	v_max_f32_e32 v86, 0, v86
	v_max_f32_e32 v87, 0, v87
	v_max_f32_e32 v88, 0, v88
	v_max_f32_e32 v89, 0, v89
	v_mul_f32_e32 v86, v86, v86
	v_mul_f32_e32 v87, v87, v87
	v_mul_f32_e32 v88, v88, v88
	v_mul_f32_e32 v89, v89, v89
	v_max_f32_e32 v82, 0, v82
	v_max_f32_e32 v83, 0, v83
	v_max_f32_e32 v84, 0, v84
	v_max_f32_e32 v85, 0, v85
	v_mul_f32_e32 v82, v82, v82
	v_mul_f32_e32 v83, v83, v83
	v_mul_f32_e32 v84, v84, v84
	v_mul_f32_e32 v85, v85, v85
	v_cvt_pk_bf16_f32 v196, v94, v95
	v_cvt_pk_bf16_f32 v197, v96, v97
	v_cvt_pk_bf16_f32 v198, v90, v91
	v_cvt_pk_bf16_f32 v199, v92, v93
	v_cvt_pk_bf16_f32 v200, v86, v87
	v_cvt_pk_bf16_f32 v201, v88, v89
	v_cvt_pk_bf16_f32 v202, v82, v83
	v_cvt_pk_bf16_f32 v203, v84, v85
	v_cmp_gt_i32_e32 vcc, s12, v206
	s_nop 0
	v_permlane16_swap_b32_e32 v196, v198
	v_permlane16_swap_b32_e32 v197, v199
	v_permlane16_swap_b32_e32 v200, v202
	v_permlane16_swap_b32_e32 v201, v203
	s_and_saveexec_b64 s[0:1], vcc
	global_store_dwordx4 v[204:205], v[196:199], off
	global_store_dwordx4 v[204:205], v[200:203], off offset:64
	s_or_b64 exec, exec, s[0:1]
	v_lshl_add_u64 v[204:205], v[204:205], 0, v[208:209]
	v_add_u32_e32 v206, 16, v206
	v_max_f32_e32 v78, 0, v78
	v_max_f32_e32 v79, 0, v79
	v_max_f32_e32 v80, 0, v80
	v_max_f32_e32 v81, 0, v81
	v_mul_f32_e32 v78, v78, v78
	v_mul_f32_e32 v79, v79, v79
	v_mul_f32_e32 v80, v80, v80
	v_mul_f32_e32 v81, v81, v81
	v_max_f32_e32 v74, 0, v74
	v_max_f32_e32 v75, 0, v75
	v_max_f32_e32 v76, 0, v76
	v_max_f32_e32 v77, 0, v77
	v_mul_f32_e32 v74, v74, v74
	v_mul_f32_e32 v75, v75, v75
	v_mul_f32_e32 v76, v76, v76
	v_mul_f32_e32 v77, v77, v77
	v_max_f32_e32 v70, 0, v70
	v_max_f32_e32 v71, 0, v71
	v_max_f32_e32 v72, 0, v72
	v_max_f32_e32 v73, 0, v73
	v_mul_f32_e32 v70, v70, v70
	v_mul_f32_e32 v71, v71, v71
	v_mul_f32_e32 v72, v72, v72
	v_mul_f32_e32 v73, v73, v73
	v_max_f32_e32 v66, 0, v66
	v_max_f32_e32 v67, 0, v67
	v_max_f32_e32 v68, 0, v68
	v_max_f32_e32 v69, 0, v69
	v_mul_f32_e32 v66, v66, v66
	v_mul_f32_e32 v67, v67, v67
	v_mul_f32_e32 v68, v68, v68
	v_mul_f32_e32 v69, v69, v69
	v_cvt_pk_bf16_f32 v196, v78, v79
	v_cvt_pk_bf16_f32 v197, v80, v81
	v_cvt_pk_bf16_f32 v198, v74, v75
	v_cvt_pk_bf16_f32 v199, v76, v77
	v_cvt_pk_bf16_f32 v200, v70, v71
	v_cvt_pk_bf16_f32 v201, v72, v73
	v_cvt_pk_bf16_f32 v202, v66, v67
	v_cvt_pk_bf16_f32 v203, v68, v69
	v_cmp_gt_i32_e32 vcc, s12, v206
	s_nop 0
	v_permlane16_swap_b32_e32 v196, v198
	v_permlane16_swap_b32_e32 v197, v199
	v_permlane16_swap_b32_e32 v200, v202
	v_permlane16_swap_b32_e32 v201, v203
	s_and_saveexec_b64 s[0:1], vcc
	global_store_dwordx4 v[204:205], v[196:199], off
	global_store_dwordx4 v[204:205], v[200:203], off offset:64
	s_or_b64 exec, exec, s[0:1]
	v_lshl_add_u64 v[204:205], v[204:205], 0, v[208:209]
	v_add_u32_e32 v206, 16, v206
	v_max_f32_e32 v62, 0, v62
	v_max_f32_e32 v63, 0, v63
	v_max_f32_e32 v64, 0, v64
	v_max_f32_e32 v65, 0, v65
	v_mul_f32_e32 v62, v62, v62
	v_mul_f32_e32 v63, v63, v63
	v_mul_f32_e32 v64, v64, v64
	v_mul_f32_e32 v65, v65, v65
	v_max_f32_e32 v58, 0, v58
	v_max_f32_e32 v59, 0, v59
	v_max_f32_e32 v60, 0, v60
	v_max_f32_e32 v61, 0, v61
	v_mul_f32_e32 v58, v58, v58
	v_mul_f32_e32 v59, v59, v59
	v_mul_f32_e32 v60, v60, v60
	v_mul_f32_e32 v61, v61, v61
	v_max_f32_e32 v54, 0, v54
	v_max_f32_e32 v55, 0, v55
	v_max_f32_e32 v56, 0, v56
	v_max_f32_e32 v57, 0, v57
	v_mul_f32_e32 v54, v54, v54
	v_mul_f32_e32 v55, v55, v55
	v_mul_f32_e32 v56, v56, v56
	v_mul_f32_e32 v57, v57, v57
	v_max_f32_e32 v50, 0, v50
	v_max_f32_e32 v51, 0, v51
	v_max_f32_e32 v52, 0, v52
	v_max_f32_e32 v53, 0, v53
	v_mul_f32_e32 v50, v50, v50
	v_mul_f32_e32 v51, v51, v51
	v_mul_f32_e32 v52, v52, v52
	v_mul_f32_e32 v53, v53, v53
	v_cvt_pk_bf16_f32 v196, v62, v63
	v_cvt_pk_bf16_f32 v197, v64, v65
	v_cvt_pk_bf16_f32 v198, v58, v59
	v_cvt_pk_bf16_f32 v199, v60, v61
	v_cvt_pk_bf16_f32 v200, v54, v55
	v_cvt_pk_bf16_f32 v201, v56, v57
	v_cvt_pk_bf16_f32 v202, v50, v51
	v_cvt_pk_bf16_f32 v203, v52, v53
	v_cmp_gt_i32_e32 vcc, s12, v206
	s_nop 0
	v_permlane16_swap_b32_e32 v196, v198
	v_permlane16_swap_b32_e32 v197, v199
	v_permlane16_swap_b32_e32 v200, v202
	v_permlane16_swap_b32_e32 v201, v203
	s_and_saveexec_b64 s[0:1], vcc
	global_store_dwordx4 v[204:205], v[196:199], off
	global_store_dwordx4 v[204:205], v[200:203], off offset:64
	s_or_b64 exec, exec, s[0:1]
	v_lshl_add_u64 v[204:205], v[204:205], 0, v[208:209]
	v_add_u32_e32 v206, 16, v206
	v_max_f32_e32 v46, 0, v46
	v_max_f32_e32 v47, 0, v47
	v_max_f32_e32 v48, 0, v48
	v_max_f32_e32 v49, 0, v49
	v_mul_f32_e32 v46, v46, v46
	v_mul_f32_e32 v47, v47, v47
	v_mul_f32_e32 v48, v48, v48
	v_mul_f32_e32 v49, v49, v49
	v_max_f32_e32 v42, 0, v42
	v_max_f32_e32 v43, 0, v43
	v_max_f32_e32 v44, 0, v44
	v_max_f32_e32 v45, 0, v45
	v_mul_f32_e32 v42, v42, v42
	v_mul_f32_e32 v43, v43, v43
	v_mul_f32_e32 v44, v44, v44
	v_mul_f32_e32 v45, v45, v45
	v_max_f32_e32 v38, 0, v38
	v_max_f32_e32 v39, 0, v39
	v_max_f32_e32 v40, 0, v40
	v_max_f32_e32 v41, 0, v41
	v_mul_f32_e32 v38, v38, v38
	v_mul_f32_e32 v39, v39, v39
	v_mul_f32_e32 v40, v40, v40
	v_mul_f32_e32 v41, v41, v41
	v_max_f32_e32 v34, 0, v34
	v_max_f32_e32 v35, 0, v35
	v_max_f32_e32 v36, 0, v36
	v_max_f32_e32 v37, 0, v37
	v_mul_f32_e32 v34, v34, v34
	v_mul_f32_e32 v35, v35, v35
	v_mul_f32_e32 v36, v36, v36
	v_mul_f32_e32 v37, v37, v37
	v_cvt_pk_bf16_f32 v196, v46, v47
	v_cvt_pk_bf16_f32 v197, v48, v49
	v_cvt_pk_bf16_f32 v198, v42, v43
	v_cvt_pk_bf16_f32 v199, v44, v45
	v_cvt_pk_bf16_f32 v200, v38, v39
	v_cvt_pk_bf16_f32 v201, v40, v41
	v_cvt_pk_bf16_f32 v202, v34, v35
	v_cvt_pk_bf16_f32 v203, v36, v37
	v_cmp_gt_i32_e32 vcc, s12, v206
	s_nop 0
	v_permlane16_swap_b32_e32 v196, v198
	v_permlane16_swap_b32_e32 v197, v199
	v_permlane16_swap_b32_e32 v200, v202
	v_permlane16_swap_b32_e32 v201, v203
	s_and_saveexec_b64 s[0:1], vcc
	global_store_dwordx4 v[204:205], v[196:199], off
	global_store_dwordx4 v[204:205], v[200:203], off offset:64
	s_or_b64 exec, exec, s[0:1]
	v_lshl_add_u64 v[204:205], v[204:205], 0, v[208:209]
	v_add_u32_e32 v206, 16, v206
	v_max_f32_e32 v30, 0, v30
	v_max_f32_e32 v31, 0, v31
	v_max_f32_e32 v32, 0, v32
	v_max_f32_e32 v33, 0, v33
	v_mul_f32_e32 v30, v30, v30
	v_mul_f32_e32 v31, v31, v31
	v_mul_f32_e32 v32, v32, v32
	v_mul_f32_e32 v33, v33, v33
	v_max_f32_e32 v26, 0, v26
	v_max_f32_e32 v27, 0, v27
	v_max_f32_e32 v28, 0, v28
	v_max_f32_e32 v29, 0, v29
	v_mul_f32_e32 v26, v26, v26
	v_mul_f32_e32 v27, v27, v27
	v_mul_f32_e32 v28, v28, v28
	v_mul_f32_e32 v29, v29, v29
	v_max_f32_e32 v22, 0, v22
	v_max_f32_e32 v23, 0, v23
	v_max_f32_e32 v24, 0, v24
	v_max_f32_e32 v25, 0, v25
	v_mul_f32_e32 v22, v22, v22
	v_mul_f32_e32 v23, v23, v23
	v_mul_f32_e32 v24, v24, v24
	v_mul_f32_e32 v25, v25, v25
	v_max_f32_e32 v14, 0, v14
	v_max_f32_e32 v15, 0, v15
	v_max_f32_e32 v16, 0, v16
	v_max_f32_e32 v17, 0, v17
	v_mul_f32_e32 v14, v14, v14
	v_mul_f32_e32 v15, v15, v15
	v_mul_f32_e32 v16, v16, v16
	v_mul_f32_e32 v17, v17, v17
	v_cvt_pk_bf16_f32 v196, v30, v31
	v_cvt_pk_bf16_f32 v197, v32, v33
	v_cvt_pk_bf16_f32 v198, v26, v27
	v_cvt_pk_bf16_f32 v199, v28, v29
	v_cvt_pk_bf16_f32 v200, v22, v23
	v_cvt_pk_bf16_f32 v201, v24, v25
	v_cvt_pk_bf16_f32 v202, v14, v15
	v_cvt_pk_bf16_f32 v203, v16, v17
	v_cmp_gt_i32_e32 vcc, s12, v206
	s_nop 0
	v_permlane16_swap_b32_e32 v196, v198
	v_permlane16_swap_b32_e32 v197, v199
	v_permlane16_swap_b32_e32 v200, v202
	v_permlane16_swap_b32_e32 v201, v203
	s_and_saveexec_b64 s[0:1], vcc
	global_store_dwordx4 v[204:205], v[196:199], off
	global_store_dwordx4 v[204:205], v[200:203], off offset:64
	s_or_b64 exec, exec, s[0:1]
	v_lshl_add_u64 v[204:205], v[204:205], 0, v[208:209]
	v_add_u32_e32 v206, 16, v206
	v_max_f32_e32 v18, 0, v18
	v_max_f32_e32 v19, 0, v19
	v_max_f32_e32 v20, 0, v20
	v_max_f32_e32 v21, 0, v21
	v_mul_f32_e32 v18, v18, v18
	v_mul_f32_e32 v19, v19, v19
	v_mul_f32_e32 v20, v20, v20
	v_mul_f32_e32 v21, v21, v21
	v_max_f32_e32 v10, 0, v10
	v_max_f32_e32 v11, 0, v11
	v_max_f32_e32 v12, 0, v12
	v_max_f32_e32 v13, 0, v13
	v_mul_f32_e32 v10, v10, v10
	v_mul_f32_e32 v11, v11, v11
	v_mul_f32_e32 v12, v12, v12
	v_mul_f32_e32 v13, v13, v13
	v_max_f32_e32 v6, 0, v6
	v_max_f32_e32 v7, 0, v7
	v_max_f32_e32 v8, 0, v8
	v_max_f32_e32 v9, 0, v9
	v_mul_f32_e32 v6, v6, v6
	v_mul_f32_e32 v7, v7, v7
	v_mul_f32_e32 v8, v8, v8
	v_mul_f32_e32 v9, v9, v9
	v_max_f32_e32 v2, 0, v2
	v_max_f32_e32 v3, 0, v3
	v_max_f32_e32 v4, 0, v4
	v_max_f32_e32 v5, 0, v5
	v_mul_f32_e32 v2, v2, v2
	v_mul_f32_e32 v3, v3, v3
	v_mul_f32_e32 v4, v4, v4
	v_mul_f32_e32 v5, v5, v5
	v_cvt_pk_bf16_f32 v196, v18, v19
	v_cvt_pk_bf16_f32 v197, v20, v21
	v_cvt_pk_bf16_f32 v198, v10, v11
	v_cvt_pk_bf16_f32 v199, v12, v13
	v_cvt_pk_bf16_f32 v200, v6, v7
	v_cvt_pk_bf16_f32 v201, v8, v9
	v_cvt_pk_bf16_f32 v202, v2, v3
	v_cvt_pk_bf16_f32 v203, v4, v5
	v_cmp_gt_i32_e32 vcc, s12, v206
	s_nop 0
	v_permlane16_swap_b32_e32 v196, v198
	v_permlane16_swap_b32_e32 v197, v199
	v_permlane16_swap_b32_e32 v200, v202
	v_permlane16_swap_b32_e32 v201, v203
	s_and_saveexec_b64 s[0:1], vcc
	global_store_dwordx4 v[204:205], v[196:199], off
	global_store_dwordx4 v[204:205], v[200:203], off offset:64
	s_or_b64 exec, exec, s[0:1]
	s_mov_b64 s[0:1], exec
	s_branch .LBB0_1579

.LBB0_3009:
	s_waitcnt vmcnt(0)
	s_waitcnt lgkmcnt(0)
	v_lshl_or_b32 v133, s16, 7, v171
	v_lshlrev_b32_e32 v0, 2, v170
	s_waitcnt lgkmcnt(0)
	s_barrier
	v_lshl_or_b32 v134, s15, 6, v0
	v_add_u32_e32 v206, s13, v133
	v_mad_i64_i32 v[204:205], s[0:1], v206, s11, 0
	v_or_b32_e32 v0, s14, v134
	v_lshlrev_b32_e32 v0, 1, v0
	v_and_b32_e32 v207, 1, v170
	v_mul_u32_u24_e32 v207, 24, v207
	v_add_u32_e32 v0, v0, v207
	v_lshl_add_u64 v[204:205], s[96:97], 0, v[204:205]
	v_lshl_add_u64 v[204:205], v[204:205], 0, v[0:1]
	s_lshl_b32 s0, s11, 4
	v_mov_b32_e32 v208, s0
	v_mov_b32_e32 v209, 0
	v_max_f32_e32 v126, 0, v126
	v_max_f32_e32 v127, 0, v127
	v_max_f32_e32 v128, 0, v128
	v_max_f32_e32 v129, 0, v129
	v_mul_f32_e32 v126, v126, v126
	v_mul_f32_e32 v127, v127, v127
	v_mul_f32_e32 v128, v128, v128
	v_mul_f32_e32 v129, v129, v129
	v_max_f32_e32 v122, 0, v122
	v_max_f32_e32 v123, 0, v123
	v_max_f32_e32 v124, 0, v124
	v_max_f32_e32 v125, 0, v125
	v_mul_f32_e32 v122, v122, v122
	v_mul_f32_e32 v123, v123, v123
	v_mul_f32_e32 v124, v124, v124
	v_mul_f32_e32 v125, v125, v125
	v_max_f32_e32 v118, 0, v118
	v_max_f32_e32 v119, 0, v119
	v_max_f32_e32 v120, 0, v120
	v_max_f32_e32 v121, 0, v121
	v_mul_f32_e32 v118, v118, v118
	v_mul_f32_e32 v119, v119, v119
	v_mul_f32_e32 v120, v120, v120
	v_mul_f32_e32 v121, v121, v121
	v_max_f32_e32 v114, 0, v114
	v_max_f32_e32 v115, 0, v115
	v_max_f32_e32 v116, 0, v116
	v_max_f32_e32 v117, 0, v117
	v_mul_f32_e32 v114, v114, v114
	v_mul_f32_e32 v115, v115, v115
	v_mul_f32_e32 v116, v116, v116
	v_mul_f32_e32 v117, v117, v117
	v_cvt_pk_bf16_f32 v196, v126, v127
	v_cvt_pk_bf16_f32 v197, v128, v129
	v_cvt_pk_bf16_f32 v198, v122, v123
	v_cvt_pk_bf16_f32 v199, v124, v125
	v_cvt_pk_bf16_f32 v200, v118, v119
	v_cvt_pk_bf16_f32 v201, v120, v121
	v_cvt_pk_bf16_f32 v202, v114, v115
	v_cvt_pk_bf16_f32 v203, v116, v117
	v_cmp_gt_i32_e32 vcc, s10, v206
	s_nop 0
	v_permlane16_swap_b32_e32 v196, v198
	v_permlane16_swap_b32_e32 v197, v199
	v_permlane16_swap_b32_e32 v200, v202
	v_permlane16_swap_b32_e32 v201, v203
	s_and_saveexec_b64 s[0:1], vcc
	global_store_dwordx4 v[204:205], v[196:199], off
	global_store_dwordx4 v[204:205], v[200:203], off offset:64
	s_or_b64 exec, exec, s[0:1]
	v_lshl_add_u64 v[204:205], v[204:205], 0, v[208:209]
	v_add_u32_e32 v206, 16, v206
	v_max_f32_e32 v110, 0, v110
	v_max_f32_e32 v111, 0, v111
	v_max_f32_e32 v112, 0, v112
	v_max_f32_e32 v113, 0, v113
	v_mul_f32_e32 v110, v110, v110
	v_mul_f32_e32 v111, v111, v111
	v_mul_f32_e32 v112, v112, v112
	v_mul_f32_e32 v113, v113, v113
	v_max_f32_e32 v106, 0, v106
	v_max_f32_e32 v107, 0, v107
	v_max_f32_e32 v108, 0, v108
	v_max_f32_e32 v109, 0, v109
	v_mul_f32_e32 v106, v106, v106
	v_mul_f32_e32 v107, v107, v107
	v_mul_f32_e32 v108, v108, v108
	v_mul_f32_e32 v109, v109, v109
	v_max_f32_e32 v102, 0, v102
	v_max_f32_e32 v103, 0, v103
	v_max_f32_e32 v104, 0, v104
	v_max_f32_e32 v105, 0, v105
	v_mul_f32_e32 v102, v102, v102
	v_mul_f32_e32 v103, v103, v103
	v_mul_f32_e32 v104, v104, v104
	v_mul_f32_e32 v105, v105, v105
	v_max_f32_e32 v98, 0, v98
	v_max_f32_e32 v99, 0, v99
	v_max_f32_e32 v100, 0, v100
	v_max_f32_e32 v101, 0, v101
	v_mul_f32_e32 v98, v98, v98
	v_mul_f32_e32 v99, v99, v99
	v_mul_f32_e32 v100, v100, v100
	v_mul_f32_e32 v101, v101, v101
	v_cvt_pk_bf16_f32 v196, v110, v111
	v_cvt_pk_bf16_f32 v197, v112, v113
	v_cvt_pk_bf16_f32 v198, v106, v107
	v_cvt_pk_bf16_f32 v199, v108, v109
	v_cvt_pk_bf16_f32 v200, v102, v103
	v_cvt_pk_bf16_f32 v201, v104, v105
	v_cvt_pk_bf16_f32 v202, v98, v99
	v_cvt_pk_bf16_f32 v203, v100, v101
	v_cmp_gt_i32_e32 vcc, s10, v206
	s_nop 0
	v_permlane16_swap_b32_e32 v196, v198
	v_permlane16_swap_b32_e32 v197, v199
	v_permlane16_swap_b32_e32 v200, v202
	v_permlane16_swap_b32_e32 v201, v203
	s_and_saveexec_b64 s[0:1], vcc
	global_store_dwordx4 v[204:205], v[196:199], off
	global_store_dwordx4 v[204:205], v[200:203], off offset:64
	s_or_b64 exec, exec, s[0:1]
	v_lshl_add_u64 v[204:205], v[204:205], 0, v[208:209]
	v_add_u32_e32 v206, 16, v206
	v_max_f32_e32 v94, 0, v94
	v_max_f32_e32 v95, 0, v95
	v_max_f32_e32 v96, 0, v96
	v_max_f32_e32 v97, 0, v97
	v_mul_f32_e32 v94, v94, v94
	v_mul_f32_e32 v95, v95, v95
	v_mul_f32_e32 v96, v96, v96
	v_mul_f32_e32 v97, v97, v97
	v_max_f32_e32 v90, 0, v90
	v_max_f32_e32 v91, 0, v91
	v_max_f32_e32 v92, 0, v92
	v_max_f32_e32 v93, 0, v93
	v_mul_f32_e32 v90, v90, v90
	v_mul_f32_e32 v91, v91, v91
	v_mul_f32_e32 v92, v92, v92
	v_mul_f32_e32 v93, v93, v93
	v_max_f32_e32 v86, 0, v86
	v_max_f32_e32 v87, 0, v87
	v_max_f32_e32 v88, 0, v88
	v_max_f32_e32 v89, 0, v89
	v_mul_f32_e32 v86, v86, v86
	v_mul_f32_e32 v87, v87, v87
	v_mul_f32_e32 v88, v88, v88
	v_mul_f32_e32 v89, v89, v89
	v_max_f32_e32 v82, 0, v82
	v_max_f32_e32 v83, 0, v83
	v_max_f32_e32 v84, 0, v84
	v_max_f32_e32 v85, 0, v85
	v_mul_f32_e32 v82, v82, v82
	v_mul_f32_e32 v83, v83, v83
	v_mul_f32_e32 v84, v84, v84
	v_mul_f32_e32 v85, v85, v85
	v_cvt_pk_bf16_f32 v196, v94, v95
	v_cvt_pk_bf16_f32 v197, v96, v97
	v_cvt_pk_bf16_f32 v198, v90, v91
	v_cvt_pk_bf16_f32 v199, v92, v93
	v_cvt_pk_bf16_f32 v200, v86, v87
	v_cvt_pk_bf16_f32 v201, v88, v89
	v_cvt_pk_bf16_f32 v202, v82, v83
	v_cvt_pk_bf16_f32 v203, v84, v85
	v_cmp_gt_i32_e32 vcc, s10, v206
	s_nop 0
	v_permlane16_swap_b32_e32 v196, v198
	v_permlane16_swap_b32_e32 v197, v199
	v_permlane16_swap_b32_e32 v200, v202
	v_permlane16_swap_b32_e32 v201, v203
	s_and_saveexec_b64 s[0:1], vcc
	global_store_dwordx4 v[204:205], v[196:199], off
	global_store_dwordx4 v[204:205], v[200:203], off offset:64
	s_or_b64 exec, exec, s[0:1]
	v_lshl_add_u64 v[204:205], v[204:205], 0, v[208:209]
	v_add_u32_e32 v206, 16, v206
	v_max_f32_e32 v78, 0, v78
	v_max_f32_e32 v79, 0, v79
	v_max_f32_e32 v80, 0, v80
	v_max_f32_e32 v81, 0, v81
	v_mul_f32_e32 v78, v78, v78
	v_mul_f32_e32 v79, v79, v79
	v_mul_f32_e32 v80, v80, v80
	v_mul_f32_e32 v81, v81, v81
	v_max_f32_e32 v74, 0, v74
	v_max_f32_e32 v75, 0, v75
	v_max_f32_e32 v76, 0, v76
	v_max_f32_e32 v77, 0, v77
	v_mul_f32_e32 v74, v74, v74
	v_mul_f32_e32 v75, v75, v75
	v_mul_f32_e32 v76, v76, v76
	v_mul_f32_e32 v77, v77, v77
	v_max_f32_e32 v70, 0, v70
	v_max_f32_e32 v71, 0, v71
	v_max_f32_e32 v72, 0, v72
	v_max_f32_e32 v73, 0, v73
	v_mul_f32_e32 v70, v70, v70
	v_mul_f32_e32 v71, v71, v71
	v_mul_f32_e32 v72, v72, v72
	v_mul_f32_e32 v73, v73, v73
	v_max_f32_e32 v66, 0, v66
	v_max_f32_e32 v67, 0, v67
	v_max_f32_e32 v68, 0, v68
	v_max_f32_e32 v69, 0, v69
	v_mul_f32_e32 v66, v66, v66
	v_mul_f32_e32 v67, v67, v67
	v_mul_f32_e32 v68, v68, v68
	v_mul_f32_e32 v69, v69, v69
	v_cvt_pk_bf16_f32 v196, v78, v79
	v_cvt_pk_bf16_f32 v197, v80, v81
	v_cvt_pk_bf16_f32 v198, v74, v75
	v_cvt_pk_bf16_f32 v199, v76, v77
	v_cvt_pk_bf16_f32 v200, v70, v71
	v_cvt_pk_bf16_f32 v201, v72, v73
	v_cvt_pk_bf16_f32 v202, v66, v67
	v_cvt_pk_bf16_f32 v203, v68, v69
	v_cmp_gt_i32_e32 vcc, s10, v206
	s_nop 0
	v_permlane16_swap_b32_e32 v196, v198
	v_permlane16_swap_b32_e32 v197, v199
	v_permlane16_swap_b32_e32 v200, v202
	v_permlane16_swap_b32_e32 v201, v203
	s_and_saveexec_b64 s[0:1], vcc
	global_store_dwordx4 v[204:205], v[196:199], off
	global_store_dwordx4 v[204:205], v[200:203], off offset:64
	s_or_b64 exec, exec, s[0:1]
	v_lshl_add_u64 v[204:205], v[204:205], 0, v[208:209]
	v_add_u32_e32 v206, 16, v206
	v_max_f32_e32 v62, 0, v62
	v_max_f32_e32 v63, 0, v63
	v_max_f32_e32 v64, 0, v64
	v_max_f32_e32 v65, 0, v65
	v_mul_f32_e32 v62, v62, v62
	v_mul_f32_e32 v63, v63, v63
	v_mul_f32_e32 v64, v64, v64
	v_mul_f32_e32 v65, v65, v65
	v_max_f32_e32 v58, 0, v58
	v_max_f32_e32 v59, 0, v59
	v_max_f32_e32 v60, 0, v60
	v_max_f32_e32 v61, 0, v61
	v_mul_f32_e32 v58, v58, v58
	v_mul_f32_e32 v59, v59, v59
	v_mul_f32_e32 v60, v60, v60
	v_mul_f32_e32 v61, v61, v61
	v_max_f32_e32 v54, 0, v54
	v_max_f32_e32 v55, 0, v55
	v_max_f32_e32 v56, 0, v56
	v_max_f32_e32 v57, 0, v57
	v_mul_f32_e32 v54, v54, v54
	v_mul_f32_e32 v55, v55, v55
	v_mul_f32_e32 v56, v56, v56
	v_mul_f32_e32 v57, v57, v57
	v_max_f32_e32 v50, 0, v50
	v_max_f32_e32 v51, 0, v51
	v_max_f32_e32 v52, 0, v52
	v_max_f32_e32 v53, 0, v53
	v_mul_f32_e32 v50, v50, v50
	v_mul_f32_e32 v51, v51, v51
	v_mul_f32_e32 v52, v52, v52
	v_mul_f32_e32 v53, v53, v53
	v_cvt_pk_bf16_f32 v196, v62, v63
	v_cvt_pk_bf16_f32 v197, v64, v65
	v_cvt_pk_bf16_f32 v198, v58, v59
	v_cvt_pk_bf16_f32 v199, v60, v61
	v_cvt_pk_bf16_f32 v200, v54, v55
	v_cvt_pk_bf16_f32 v201, v56, v57
	v_cvt_pk_bf16_f32 v202, v50, v51
	v_cvt_pk_bf16_f32 v203, v52, v53
	v_cmp_gt_i32_e32 vcc, s10, v206
	s_nop 0
	v_permlane16_swap_b32_e32 v196, v198
	v_permlane16_swap_b32_e32 v197, v199
	v_permlane16_swap_b32_e32 v200, v202
	v_permlane16_swap_b32_e32 v201, v203
	s_and_saveexec_b64 s[0:1], vcc
	global_store_dwordx4 v[204:205], v[196:199], off
	global_store_dwordx4 v[204:205], v[200:203], off offset:64
	s_or_b64 exec, exec, s[0:1]
	v_lshl_add_u64 v[204:205], v[204:205], 0, v[208:209]
	v_add_u32_e32 v206, 16, v206
	v_max_f32_e32 v46, 0, v46
	v_max_f32_e32 v47, 0, v47
	v_max_f32_e32 v48, 0, v48
	v_max_f32_e32 v49, 0, v49
	v_mul_f32_e32 v46, v46, v46
	v_mul_f32_e32 v47, v47, v47
	v_mul_f32_e32 v48, v48, v48
	v_mul_f32_e32 v49, v49, v49
	v_max_f32_e32 v42, 0, v42
	v_max_f32_e32 v43, 0, v43
	v_max_f32_e32 v44, 0, v44
	v_max_f32_e32 v45, 0, v45
	v_mul_f32_e32 v42, v42, v42
	v_mul_f32_e32 v43, v43, v43
	v_mul_f32_e32 v44, v44, v44
	v_mul_f32_e32 v45, v45, v45
	v_max_f32_e32 v38, 0, v38
	v_max_f32_e32 v39, 0, v39
	v_max_f32_e32 v40, 0, v40
	v_max_f32_e32 v41, 0, v41
	v_mul_f32_e32 v38, v38, v38
	v_mul_f32_e32 v39, v39, v39
	v_mul_f32_e32 v40, v40, v40
	v_mul_f32_e32 v41, v41, v41
	v_max_f32_e32 v34, 0, v34
	v_max_f32_e32 v35, 0, v35
	v_max_f32_e32 v36, 0, v36
	v_max_f32_e32 v37, 0, v37
	v_mul_f32_e32 v34, v34, v34
	v_mul_f32_e32 v35, v35, v35
	v_mul_f32_e32 v36, v36, v36
	v_mul_f32_e32 v37, v37, v37
	v_cvt_pk_bf16_f32 v196, v46, v47
	v_cvt_pk_bf16_f32 v197, v48, v49
	v_cvt_pk_bf16_f32 v198, v42, v43
	v_cvt_pk_bf16_f32 v199, v44, v45
	v_cvt_pk_bf16_f32 v200, v38, v39
	v_cvt_pk_bf16_f32 v201, v40, v41
	v_cvt_pk_bf16_f32 v202, v34, v35
	v_cvt_pk_bf16_f32 v203, v36, v37
	v_cmp_gt_i32_e32 vcc, s10, v206
	s_nop 0
	v_permlane16_swap_b32_e32 v196, v198
	v_permlane16_swap_b32_e32 v197, v199
	v_permlane16_swap_b32_e32 v200, v202
	v_permlane16_swap_b32_e32 v201, v203
	s_and_saveexec_b64 s[0:1], vcc
	global_store_dwordx4 v[204:205], v[196:199], off
	global_store_dwordx4 v[204:205], v[200:203], off offset:64
	s_or_b64 exec, exec, s[0:1]
	v_lshl_add_u64 v[204:205], v[204:205], 0, v[208:209]
	v_add_u32_e32 v206, 16, v206
	v_max_f32_e32 v30, 0, v30
	v_max_f32_e32 v31, 0, v31
	v_max_f32_e32 v32, 0, v32
	v_max_f32_e32 v33, 0, v33
	v_mul_f32_e32 v30, v30, v30
	v_mul_f32_e32 v31, v31, v31
	v_mul_f32_e32 v32, v32, v32
	v_mul_f32_e32 v33, v33, v33
	v_max_f32_e32 v26, 0, v26
	v_max_f32_e32 v27, 0, v27
	v_max_f32_e32 v28, 0, v28
	v_max_f32_e32 v29, 0, v29
	v_mul_f32_e32 v26, v26, v26
	v_mul_f32_e32 v27, v27, v27
	v_mul_f32_e32 v28, v28, v28
	v_mul_f32_e32 v29, v29, v29
	v_max_f32_e32 v22, 0, v22
	v_max_f32_e32 v23, 0, v23
	v_max_f32_e32 v24, 0, v24
	v_max_f32_e32 v25, 0, v25
	v_mul_f32_e32 v22, v22, v22
	v_mul_f32_e32 v23, v23, v23
	v_mul_f32_e32 v24, v24, v24
	v_mul_f32_e32 v25, v25, v25
	v_max_f32_e32 v14, 0, v14
	v_max_f32_e32 v15, 0, v15
	v_max_f32_e32 v16, 0, v16
	v_max_f32_e32 v17, 0, v17
	v_mul_f32_e32 v14, v14, v14
	v_mul_f32_e32 v15, v15, v15
	v_mul_f32_e32 v16, v16, v16
	v_mul_f32_e32 v17, v17, v17
	v_cvt_pk_bf16_f32 v196, v30, v31
	v_cvt_pk_bf16_f32 v197, v32, v33
	v_cvt_pk_bf16_f32 v198, v26, v27
	v_cvt_pk_bf16_f32 v199, v28, v29
	v_cvt_pk_bf16_f32 v200, v22, v23
	v_cvt_pk_bf16_f32 v201, v24, v25
	v_cvt_pk_bf16_f32 v202, v14, v15
	v_cvt_pk_bf16_f32 v203, v16, v17
	v_cmp_gt_i32_e32 vcc, s10, v206
	s_nop 0
	v_permlane16_swap_b32_e32 v196, v198
	v_permlane16_swap_b32_e32 v197, v199
	v_permlane16_swap_b32_e32 v200, v202
	v_permlane16_swap_b32_e32 v201, v203
	s_and_saveexec_b64 s[0:1], vcc
	global_store_dwordx4 v[204:205], v[196:199], off
	global_store_dwordx4 v[204:205], v[200:203], off offset:64
	s_or_b64 exec, exec, s[0:1]
	v_lshl_add_u64 v[204:205], v[204:205], 0, v[208:209]
	v_add_u32_e32 v206, 16, v206
	v_max_f32_e32 v18, 0, v18
	v_max_f32_e32 v19, 0, v19
	v_max_f32_e32 v20, 0, v20
	v_max_f32_e32 v21, 0, v21
	v_mul_f32_e32 v18, v18, v18
	v_mul_f32_e32 v19, v19, v19
	v_mul_f32_e32 v20, v20, v20
	v_mul_f32_e32 v21, v21, v21
	v_max_f32_e32 v10, 0, v10
	v_max_f32_e32 v11, 0, v11
	v_max_f32_e32 v12, 0, v12
	v_max_f32_e32 v13, 0, v13
	v_mul_f32_e32 v10, v10, v10
	v_mul_f32_e32 v11, v11, v11
	v_mul_f32_e32 v12, v12, v12
	v_mul_f32_e32 v13, v13, v13
	v_max_f32_e32 v6, 0, v6
	v_max_f32_e32 v7, 0, v7
	v_max_f32_e32 v8, 0, v8
	v_max_f32_e32 v9, 0, v9
	v_mul_f32_e32 v6, v6, v6
	v_mul_f32_e32 v7, v7, v7
	v_mul_f32_e32 v8, v8, v8
	v_mul_f32_e32 v9, v9, v9
	v_max_f32_e32 v2, 0, v2
	v_max_f32_e32 v3, 0, v3
	v_max_f32_e32 v4, 0, v4
	v_max_f32_e32 v5, 0, v5
	v_mul_f32_e32 v2, v2, v2
	v_mul_f32_e32 v3, v3, v3
	v_mul_f32_e32 v4, v4, v4
	v_mul_f32_e32 v5, v5, v5
	v_cvt_pk_bf16_f32 v196, v18, v19
	v_cvt_pk_bf16_f32 v197, v20, v21
	v_cvt_pk_bf16_f32 v198, v10, v11
	v_cvt_pk_bf16_f32 v199, v12, v13
	v_cvt_pk_bf16_f32 v200, v6, v7
	v_cvt_pk_bf16_f32 v201, v8, v9
	v_cvt_pk_bf16_f32 v202, v2, v3
	v_cvt_pk_bf16_f32 v203, v4, v5
	v_cmp_gt_i32_e32 vcc, s10, v206
	s_nop 0
	v_permlane16_swap_b32_e32 v196, v198
	v_permlane16_swap_b32_e32 v197, v199
	v_permlane16_swap_b32_e32 v200, v202
	v_permlane16_swap_b32_e32 v201, v203
	s_and_saveexec_b64 s[0:1], vcc
	global_store_dwordx4 v[204:205], v[196:199], off
	global_store_dwordx4 v[204:205], v[200:203], off offset:64
	s_or_b64 exec, exec, s[0:1]
	s_mov_b64 s[0:1], exec
	s_branch .LBB0_3004

	.amdhsa_kernel _Z4mega6Params
		.amdhsa_group_segment_fixed_size 0
		.amdhsa_private_segment_fixed_size 0
		.amdhsa_kernarg_size 568
		.amdhsa_user_sgpr_count 2
		.amdhsa_user_sgpr_dispatch_ptr 0
		.amdhsa_user_sgpr_queue_ptr 0
		.amdhsa_user_sgpr_kernarg_segment_ptr 1
		.amdhsa_user_sgpr_dispatch_id 0
		.amdhsa_user_sgpr_kernarg_preload_length 0
		.amdhsa_user_sgpr_kernarg_preload_offset 0
		.amdhsa_user_sgpr_private_segment_size 0
		.amdhsa_uses_dynamic_stack 0
		.amdhsa_enable_private_segment 0
		.amdhsa_system_sgpr_workgroup_id_x 1
		.amdhsa_system_sgpr_workgroup_id_y 0
		.amdhsa_system_sgpr_workgroup_id_z 0
		.amdhsa_system_sgpr_workgroup_info 0
		.amdhsa_system_vgpr_workitem_id 2
		.amdhsa_next_free_vgpr 216
		.amdhsa_next_free_sgpr 98
		.amdhsa_accum_offset 216
		.amdhsa_reserve_vcc 1
		.amdhsa_float_round_mode_32 0
		.amdhsa_float_round_mode_16_64 0
		.amdhsa_float_denorm_mode_32 3
		.amdhsa_float_denorm_mode_16_64 3
		.amdhsa_dx10_clamp 1
		.amdhsa_ieee_mode 1
		.amdhsa_fp16_overflow 0
		.amdhsa_tg_split 0
		.amdhsa_exception_fp_ieee_invalid_op 0
		.amdhsa_exception_fp_denorm_src 0
		.amdhsa_exception_fp_ieee_div_zero 0
		.amdhsa_exception_fp_ieee_overflow 0
		.amdhsa_exception_fp_ieee_underflow 0
		.amdhsa_exception_fp_ieee_inexact 0
		.amdhsa_exception_int_div_zero 0
	.end_amdhsa_kernel

.Lfunc_end0:
	.size	_Z4mega6Params, .Lfunc_end0-_Z4mega6Params
	.set _Z4mega6Params.num_vgpr, 216
	.set _Z4mega6Params.num_agpr, 0
	.set _Z4mega6Params.numbered_sgpr, 98
	.set _Z4mega6Params.num_named_barrier, 0
	.set _Z4mega6Params.private_seg_size, 0
	.set _Z4mega6Params.uses_vcc, 1
	.set _Z4mega6Params.uses_flat_scratch, 0
	.set _Z4mega6Params.has_dyn_sized_stack, 0
	.set _Z4mega6Params.has_recursion, 0
	.set _Z4mega6Params.has_indirect_call, 0

amdhsa.kernels:
  - .agpr_count:     0
    .args:
      - .offset:         0
        .size:           312
        .value_kind:     by_value
      - .offset:         312
        .size:           4
        .value_kind:     hidden_block_count_x
      - .offset:         316
        .size:           4
        .value_kind:     hidden_block_count_y
      - .offset:         320
        .size:           4
        .value_kind:     hidden_block_count_z
      - .offset:         324
        .size:           2
        .value_kind:     hidden_group_size_x
      - .offset:         326
        .size:           2
        .value_kind:     hidden_group_size_y
      - .offset:         328
        .size:           2
        .value_kind:     hidden_group_size_z
      - .offset:         330
        .size:           2
        .value_kind:     hidden_remainder_x
      - .offset:         332
        .size:           2
        .value_kind:     hidden_remainder_y
      - .offset:         334
        .size:           2
        .value_kind:     hidden_remainder_z
      - .offset:         352
        .size:           8
        .value_kind:     hidden_global_offset_x
      - .offset:         360
        .size:           8
        .value_kind:     hidden_global_offset_y
      - .offset:         368
        .size:           8
        .value_kind:     hidden_global_offset_z
      - .offset:         376
        .size:           2
        .value_kind:     hidden_grid_dims
      - .offset:         400
        .size:           8
        .value_kind:     hidden_multigrid_sync_arg
      - .offset:         432
        .size:           4
        .value_kind:     hidden_dynamic_lds_size
    .group_segment_fixed_size: 0
    .kernarg_segment_align: 8
    .kernarg_segment_size: 568
    .language:       OpenCL C
    .language_version:
      - 2
      - 0
    .max_flat_workgroup_size: 512
    .name:           _Z4mega6Params
    .private_segment_fixed_size: 0
    .sgpr_count:     104
    .sgpr_spill_count: 60
    .symbol:         _Z4mega6Params.kd
    .uniform_work_group_size: 1
    .uses_dynamic_stack: false
    .vgpr_count:     216
    .vgpr_spill_count: 0
    .wavefront_size: 64
